# GQA + MLA attention inner loops hand software-pipelined (exp/cvt overlapped with MFMA, LDS fragment reloads behind consuming MFMAs)
# speedup vs baseline: 1.0318x; 1.0318x over previous
; #define MFMA32(a, b, c) __builtin_amdgcn_mfma_f32_32x32x16_bf16((a), (b), (c), 0, 0, 0)
; DI bf16x8 cat4(s16x4 lo, s16x4 hi) { return __builtin_shufflevector(lo, hi, 0, 1, 2, 3, 4, 5, 6, 7); }
; template <int DK>
; DI void attn_dense_item(const u16* __restrict__ Qh, const u16* __restrict__ Kh, const u16* __restrict__ Vh,
;                         const u16* __restrict__ gate, u16* __restrict__ yout, char* lds) {
;     ...
;     char* buf = lds + cur * BUF;
;     if (j + 1 < NT) stage(j + 1, lds + (cur ^ 1) * BUF);
; #pragma unroll
;     for (int kb = 0; kb < KT / 32; ++kb) {
;       f32x16 S0, S1;
; #pragma unroll
;       for (int i = 0; i < 16; ++i) { S0[i] = 0.f; S1[i] = 0.f; }
; #pragma unroll
;       for (int s = 0; s < NS; ++s) {
;         const bf16x8 kf = *(const bf16x8*)(buf + koff(kb * 32 + r32, 2 * s + h));
;         S0 = MFMA32(kf, qf[0][s], S0);
;         S1 = MFMA32(kf, qf[1][s], S1);
;       }
; #pragma unroll
;       for (int i = 0; i < 16; ++i) S0[i] = __builtin_amdgcn_exp2f(S0[i]);
; #pragma unroll
;       for (int i = 0; i < 16; ++i) S1[i] = __builtin_amdgcn_exp2f(S1[i]);
;       bf16x8 pf0[2], pf1[2];
; #pragma unroll
;       for (int st = 0; st < 2; ++st) {
;         pf0[st] = pack8(S0[8 * st], S0[8 * st + 1], S0[8 * st + 2], S0[8 * st + 3], S0[8 * st + 4], S0[8 * st + 5], S0[8 * st + 6], S0[8 * st + 7]);
;         pf1[st] = pack8(S1[8 * st], S1[8 * st + 1], S1[8 * st + 2], S1[8 * st + 3], S1[8 * st + 4], S1[8 * st + 5], S1[8 * st + 6], S1[8 * st + 7]);
;       }
; #pragma unroll
;       for (int st = 0; st < 2; ++st) {
;         L0 = __builtin_amdgcn_mfma_f32_16x16x32_bf16(aones, pf0[st], L0, 0, 0, 0);
;         L1 = __builtin_amdgcn_mfma_f32_16x16x32_bf16(aones, pf1[st], L1, 0, 0, 0);
;       }
; #pragma unroll
;       for (int st = 0; st < 2; ++st)
; #pragma unroll
;         for (int db = 0; db < 2; ++db) {
;           const char* vp = buf + vbase[db] + (kb * 32 + st * 16) * 128;
;           const bf16x8 vf = cat4(trread(vp), trread(vp + 8 * 128));
;           O[0][db] = MFMA32(vf, pf0[st], O[0][db]);
;           O[1][db] = MFMA32(vf, pf1[st], O[1][db]);
;         }
;     }
.LBB0_107:
	s_mul_i32 s3, s3, 0x14000
	s_add_i32 s0, s0, -1
	v_lshl_add_u64 v[176:177], v[176:177], 0, s[88:89]
	v_lshl_add_u64 v[178:179], v[178:179], 0, s[94:95]
	v_lshl_add_u64 v[180:181], v[180:181], 0, s[94:95]
	v_lshl_add_u64 v[182:183], v[182:183], 0, s[94:95]
	v_lshl_add_u64 v[184:185], v[184:185], 0, s[94:95]
	v_lshl_add_u64 v[186:187], v[186:187], 0, s[94:95]
	v_lshl_add_u64 v[188:189], v[188:189], 0, s[94:95]
	v_or_b32_e32 v167, s3, v219
	v_add_u32_e32 v164, v167, v220
	v_add_u32_e32 v227, v167, v221
	v_add_u32_e32 v244, v167, v222
	v_add_u32_e32 v245, v167, v223
	v_add_u32_e32 v216, v167, v224
	v_add_u32_e32 v192, v167, v225
	v_or_b32_e32 v193, s3, v173
	v_or_b32_e32 v199, s3, v226
	v_add_u32_e32 v193, 0x8000, v193
	v_add_u32_e32 v199, 0x8000, v199
	ds_read_b128 v[156:159], v164 offset:0
	ds_read_b128 v[160:163], v227 offset:0
	ds_read_b128 v[228:231], v244 offset:0
	ds_read_b128 v[232:235], v245 offset:0
	ds_read_b128 v[236:239], v216 offset:0
	ds_read_b128 v[240:243], v192 offset:0
	ds_read_b64_tr_b16 v[200:201], v193 offset:16384
	ds_read_b64_tr_b16 v[202:203], v193 offset:17408
	ds_read_b64_tr_b16 v[204:205], v199 offset:16384
	ds_read_b64_tr_b16 v[206:207], v199 offset:17408
	ds_read_b64_tr_b16 v[208:209], v193 offset:18432
	ds_read_b64_tr_b16 v[210:211], v193 offset:19456
	ds_read_b64_tr_b16 v[212:213], v199 offset:18432
	ds_read_b64_tr_b16 v[214:215], v199 offset:19456
	s_waitcnt lgkmcnt(13)
	v_mfma_f32_32x32x16_bf16 v[64:79], v[156:159], v[80:83], 0
	s_waitcnt lgkmcnt(12)
	v_mfma_f32_32x32x16_bf16 v[64:79], v[160:163], v[84:87], v[64:79]
	s_waitcnt lgkmcnt(11)
	v_mfma_f32_32x32x16_bf16 v[64:79], v[228:231], v[88:91], v[64:79]
	s_waitcnt lgkmcnt(10)
	v_mfma_f32_32x32x16_bf16 v[64:79], v[232:235], v[92:95], v[64:79]
	s_waitcnt lgkmcnt(9)
	v_mfma_f32_32x32x16_bf16 v[64:79], v[236:239], v[96:99], v[64:79]
	s_waitcnt lgkmcnt(8)
	v_mfma_f32_32x32x16_bf16 v[64:79], v[240:243], v[100:103], v[64:79]
	v_mfma_f32_32x32x16_bf16 v[140:155], v[156:159], v[104:107], 0
	ds_read_b128 v[156:159], v164 offset:6144
	v_mfma_f32_32x32x16_bf16 v[140:155], v[160:163], v[108:111], v[140:155]
	ds_read_b128 v[160:163], v227 offset:6144
	v_mfma_f32_32x32x16_bf16 v[140:155], v[228:231], v[112:115], v[140:155]
	ds_read_b128 v[228:231], v244 offset:6144
	v_mfma_f32_32x32x16_bf16 v[140:155], v[232:235], v[116:119], v[140:155]
	ds_read_b128 v[232:235], v245 offset:6144
	v_mfma_f32_32x32x16_bf16 v[140:155], v[236:239], v[120:123], v[140:155]
	ds_read_b128 v[236:239], v216 offset:6144
	v_mfma_f32_32x32x16_bf16 v[140:155], v[240:243], v[124:127], v[140:155]
	ds_read_b128 v[240:243], v192 offset:6144
	v_exp_f32_e32 v64, v64
	v_exp_f32_e32 v65, v65
	v_exp_f32_e32 v66, v66
	v_exp_f32_e32 v67, v67
	v_exp_f32_e32 v68, v68
	v_exp_f32_e32 v69, v69
	v_exp_f32_e32 v70, v70
	v_exp_f32_e32 v71, v71
	v_exp_f32_e32 v72, v72
	v_exp_f32_e32 v73, v73
	v_exp_f32_e32 v74, v74
	v_exp_f32_e32 v75, v75
	v_exp_f32_e32 v76, v76
	v_exp_f32_e32 v77, v77
	v_exp_f32_e32 v78, v78
	v_exp_f32_e32 v79, v79
	v_cvt_pk_bf16_f32 v64, v64, v65
	v_cvt_pk_bf16_f32 v65, v66, v67
	v_cvt_pk_bf16_f32 v66, v68, v69
	v_cvt_pk_bf16_f32 v67, v70, v71
	v_cvt_pk_bf16_f32 v68, v72, v73
	v_cvt_pk_bf16_f32 v69, v74, v75
	v_cvt_pk_bf16_f32 v70, v76, v77
	v_cvt_pk_bf16_f32 v71, v78, v79
	s_waitcnt lgkmcnt(6)
	v_mfma_f32_32x32x16_bf16 v[48:63], v[200:203], v[64:67], v[48:63]
	v_mfma_f32_32x32x16_bf16 v[32:47], v[204:207], v[64:67], v[32:47]
	v_mfma_f32_32x32x16_bf16 v[48:63], v[208:211], v[68:71], v[48:63]
	v_mfma_f32_32x32x16_bf16 v[32:47], v[212:215], v[68:71], v[32:47]
	v_mfma_f32_16x16x32_bf16 v[136:139], v[128:131], v[64:67], v[136:139]
	v_mfma_f32_16x16x32_bf16 v[136:139], v[128:131], v[68:71], v[136:139]
	s_waitcnt lgkmcnt(5)
	v_mfma_f32_32x32x16_bf16 v[64:79], v[156:159], v[80:83], 0
	s_nop 2
	v_exp_f32_e32 v140, v140
	v_exp_f32_e32 v141, v141
	v_exp_f32_e32 v142, v142
	v_exp_f32_e32 v143, v143
	s_waitcnt lgkmcnt(4)
	v_mfma_f32_32x32x16_bf16 v[64:79], v[160:163], v[84:87], v[64:79]
	v_exp_f32_e32 v144, v144
	v_exp_f32_e32 v145, v145
	v_exp_f32_e32 v146, v146
	v_exp_f32_e32 v147, v147
	s_waitcnt lgkmcnt(3)
	v_mfma_f32_32x32x16_bf16 v[64:79], v[228:231], v[88:91], v[64:79]
	v_exp_f32_e32 v148, v148
	v_exp_f32_e32 v149, v149
	v_exp_f32_e32 v150, v150
	v_exp_f32_e32 v151, v151
	s_waitcnt lgkmcnt(2)
	v_mfma_f32_32x32x16_bf16 v[64:79], v[232:235], v[92:95], v[64:79]
	v_exp_f32_e32 v152, v152
	v_exp_f32_e32 v153, v153
	v_exp_f32_e32 v154, v154
	v_exp_f32_e32 v155, v155
	s_waitcnt lgkmcnt(1)
	v_mfma_f32_32x32x16_bf16 v[64:79], v[236:239], v[96:99], v[64:79]
	v_cvt_pk_bf16_f32 v140, v140, v141
	v_cvt_pk_bf16_f32 v141, v142, v143
	v_cvt_pk_bf16_f32 v142, v144, v145
	v_cvt_pk_bf16_f32 v143, v146, v147
	s_waitcnt lgkmcnt(0)
; #define MFMA32(a, b, c) __builtin_amdgcn_mfma_f32_32x32x16_bf16((a), (b), (c), 0, 0, 0)
; DI bf16x8 cat4(s16x4 lo, s16x4 hi) { return __builtin_shufflevector(lo, hi, 0, 1, 2, 3, 4, 5, 6, 7); }
; template <int DK>
; DI void attn_dense_item(const u16* __restrict__ Qh, const u16* __restrict__ Kh, const u16* __restrict__ Vh,
;                         const u16* __restrict__ gate, u16* __restrict__ yout, char* lds) {
;     ...
;     for (int kb = 0; kb < KT / 32; ++kb) {
;       f32x16 S0, S1;
; #pragma unroll
;       for (int i = 0; i < 16; ++i) { S0[i] = 0.f; S1[i] = 0.f; }
; #pragma unroll
;       for (int s = 0; s < NS; ++s) {
;         const bf16x8 kf = *(const bf16x8*)(buf + koff(kb * 32 + r32, 2 * s + h));
;         S0 = MFMA32(kf, qf[0][s], S0);
;         S1 = MFMA32(kf, qf[1][s], S1);
;       }
; #pragma unroll
;       for (int i = 0; i < 16; ++i) S0[i] = __builtin_amdgcn_exp2f(S0[i]);
; #pragma unroll
;       for (int i = 0; i < 16; ++i) S1[i] = __builtin_amdgcn_exp2f(S1[i]);
;       bf16x8 pf0[2], pf1[2];
; #pragma unroll
;       for (int st = 0; st < 2; ++st) {
;         pf0[st] = pack8(S0[8 * st], S0[8 * st + 1], S0[8 * st + 2], S0[8 * st + 3], S0[8 * st + 4], S0[8 * st + 5], S0[8 * st + 6], S0[8 * st + 7]);
;         pf1[st] = pack8(S1[8 * st], S1[8 * st + 1], S1[8 * st + 2], S1[8 * st + 3], S1[8 * st + 4], S1[8 * st + 5], S1[8 * st + 6], S1[8 * st + 7]);
;       }
; #pragma unroll
;       for (int st = 0; st < 2; ++st) {
;         L0 = __builtin_amdgcn_mfma_f32_16x16x32_bf16(aones, pf0[st], L0, 0, 0, 0);
;         L1 = __builtin_amdgcn_mfma_f32_16x16x32_bf16(aones, pf1[st], L1, 0, 0, 0);
;       }
; #pragma unroll
;       for (int st = 0; st < 2; ++st)
; #pragma unroll
;         for (int db = 0; db < 2; ++db) {
;           const char* vp = buf + vbase[db] + (kb * 32 + st * 16) * 128;
;           const bf16x8 vf = cat4(trread(vp), trread(vp + 8 * 128));
;           O[0][db] = MFMA32(vf, pf0[st], O[0][db]);
;           O[1][db] = MFMA32(vf, pf1[st], O[1][db]);
;         }
	v_mfma_f32_32x32x16_bf16 v[64:79], v[240:243], v[100:103], v[64:79]
	v_cvt_pk_bf16_f32 v144, v148, v149
	v_cvt_pk_bf16_f32 v145, v150, v151
	v_cvt_pk_bf16_f32 v146, v152, v153
	v_cvt_pk_bf16_f32 v147, v154, v155
	v_mfma_f32_32x32x16_bf16 v[16:31], v[200:203], v[140:143], v[16:31]
	ds_read_b64_tr_b16 v[200:201], v193 offset:20480
	ds_read_b64_tr_b16 v[202:203], v193 offset:21504
	v_mfma_f32_32x32x16_bf16 v[0:15], v[204:207], v[140:143], v[0:15]
	ds_read_b64_tr_b16 v[204:205], v199 offset:20480
	ds_read_b64_tr_b16 v[206:207], v199 offset:21504
	v_mfma_f32_32x32x16_bf16 v[16:31], v[208:211], v[144:147], v[16:31]
	ds_read_b64_tr_b16 v[208:209], v193 offset:22528
	ds_read_b64_tr_b16 v[210:211], v193 offset:23552
	v_mfma_f32_32x32x16_bf16 v[0:15], v[212:215], v[144:147], v[0:15]
	ds_read_b64_tr_b16 v[212:213], v199 offset:22528
	ds_read_b64_tr_b16 v[214:215], v199 offset:23552
	v_mfma_f32_16x16x32_bf16 v[132:135], v[128:131], v[140:143], v[132:135]
	v_mfma_f32_16x16x32_bf16 v[132:135], v[128:131], v[144:147], v[132:135]
	v_mfma_f32_32x32x16_bf16 v[140:155], v[156:159], v[104:107], 0
	ds_read_b128 v[156:159], v164 offset:12288
	v_exp_f32_e32 v64, v64
	v_exp_f32_e32 v65, v65
	v_exp_f32_e32 v66, v66
	v_exp_f32_e32 v67, v67
	v_mfma_f32_32x32x16_bf16 v[140:155], v[160:163], v[108:111], v[140:155]
	ds_read_b128 v[160:163], v227 offset:12288
	v_exp_f32_e32 v68, v68
	v_exp_f32_e32 v69, v69
	v_exp_f32_e32 v70, v70
	v_exp_f32_e32 v71, v71
	v_mfma_f32_32x32x16_bf16 v[140:155], v[228:231], v[112:115], v[140:155]
	ds_read_b128 v[228:231], v244 offset:12288
	v_exp_f32_e32 v72, v72
	v_exp_f32_e32 v73, v73
	v_exp_f32_e32 v74, v74
	v_exp_f32_e32 v75, v75
	v_mfma_f32_32x32x16_bf16 v[140:155], v[232:235], v[116:119], v[140:155]
	ds_read_b128 v[232:235], v245 offset:12288
	v_exp_f32_e32 v76, v76
	v_exp_f32_e32 v77, v77
	v_exp_f32_e32 v78, v78
	v_exp_f32_e32 v79, v79
	v_mfma_f32_32x32x16_bf16 v[140:155], v[236:239], v[120:123], v[140:155]
	ds_read_b128 v[236:239], v216 offset:12288
	v_cvt_pk_bf16_f32 v64, v64, v65
	v_cvt_pk_bf16_f32 v65, v66, v67
	v_cvt_pk_bf16_f32 v66, v68, v69
	v_cvt_pk_bf16_f32 v67, v70, v71
	v_mfma_f32_32x32x16_bf16 v[140:155], v[240:243], v[124:127], v[140:155]
	ds_read_b128 v[240:243], v192 offset:12288
	v_cvt_pk_bf16_f32 v68, v72, v73
	v_cvt_pk_bf16_f32 v69, v74, v75
	v_cvt_pk_bf16_f32 v70, v76, v77
	v_cvt_pk_bf16_f32 v71, v78, v79
	s_waitcnt lgkmcnt(12)
	v_mfma_f32_32x32x16_bf16 v[48:63], v[200:203], v[64:67], v[48:63]
	s_waitcnt lgkmcnt(10)
	v_mfma_f32_32x32x16_bf16 v[32:47], v[204:207], v[64:67], v[32:47]
	s_waitcnt lgkmcnt(8)
	v_mfma_f32_32x32x16_bf16 v[48:63], v[208:211], v[68:71], v[48:63]
	s_waitcnt lgkmcnt(6)
	v_mfma_f32_32x32x16_bf16 v[32:47], v[212:215], v[68:71], v[32:47]
	v_mfma_f32_16x16x32_bf16 v[136:139], v[128:131], v[64:67], v[136:139]
	v_mfma_f32_16x16x32_bf16 v[136:139], v[128:131], v[68:71], v[136:139]
	s_waitcnt lgkmcnt(5)
	v_mfma_f32_32x32x16_bf16 v[64:79], v[156:159], v[80:83], 0
	v_exp_f32_e32 v140, v140
	v_exp_f32_e32 v141, v141
	v_exp_f32_e32 v142, v142
	v_exp_f32_e32 v143, v143
	s_waitcnt lgkmcnt(4)
	v_mfma_f32_32x32x16_bf16 v[64:79], v[160:163], v[84:87], v[64:79]
	v_exp_f32_e32 v144, v144
	v_exp_f32_e32 v145, v145
	v_exp_f32_e32 v146, v146
	v_exp_f32_e32 v147, v147
	s_waitcnt lgkmcnt(3)
	v_mfma_f32_32x32x16_bf16 v[64:79], v[228:231], v[88:91], v[64:79]
	v_exp_f32_e32 v148, v148
	v_exp_f32_e32 v149, v149
	v_exp_f32_e32 v150, v150
	v_exp_f32_e32 v151, v151
	s_waitcnt lgkmcnt(2)
	v_mfma_f32_32x32x16_bf16 v[64:79], v[232:235], v[92:95], v[64:79]
	v_exp_f32_e32 v152, v152
	v_exp_f32_e32 v153, v153
	v_exp_f32_e32 v154, v154
	v_exp_f32_e32 v155, v155
	s_waitcnt lgkmcnt(1)
	v_mfma_f32_32x32x16_bf16 v[64:79], v[236:239], v[96:99], v[64:79]
	v_cvt_pk_bf16_f32 v140, v140, v141
	v_cvt_pk_bf16_f32 v141, v142, v143
	v_cvt_pk_bf16_f32 v142, v144, v145
	v_cvt_pk_bf16_f32 v143, v146, v147
	s_waitcnt lgkmcnt(0)
	v_mfma_f32_32x32x16_bf16 v[64:79], v[240:243], v[100:103], v[64:79]
	v_cvt_pk_bf16_f32 v144, v148, v149
	v_cvt_pk_bf16_f32 v145, v150, v151
	v_cvt_pk_bf16_f32 v146, v152, v153
	v_cvt_pk_bf16_f32 v147, v154, v155
	v_mfma_f32_32x32x16_bf16 v[16:31], v[200:203], v[140:143], v[16:31]
	ds_read_b64_tr_b16 v[200:201], v193 offset:24576
	ds_read_b64_tr_b16 v[202:203], v193 offset:25600
	v_mfma_f32_32x32x16_bf16 v[0:15], v[204:207], v[140:143], v[0:15]
	ds_read_b64_tr_b16 v[204:205], v199 offset:24576
	ds_read_b64_tr_b16 v[206:207], v199 offset:25600
	v_mfma_f32_32x32x16_bf16 v[16:31], v[208:211], v[144:147], v[16:31]
	ds_read_b64_tr_b16 v[208:209], v193 offset:26624
	ds_read_b64_tr_b16 v[210:211], v193 offset:27648
	v_mfma_f32_32x32x16_bf16 v[0:15], v[212:215], v[144:147], v[0:15]
	ds_read_b64_tr_b16 v[212:213], v199 offset:26624
	ds_read_b64_tr_b16 v[214:215], v199 offset:27648
	v_mfma_f32_16x16x32_bf16 v[132:135], v[128:131], v[140:143], v[132:135]
	v_mfma_f32_16x16x32_bf16 v[132:135], v[128:131], v[144:147], v[132:135]
	v_mfma_f32_32x32x16_bf16 v[140:155], v[156:159], v[104:107], 0
	ds_read_b128 v[156:159], v164 offset:18432
	v_exp_f32_e32 v64, v64
	v_exp_f32_e32 v65, v65
	v_exp_f32_e32 v66, v66
	v_exp_f32_e32 v67, v67
	v_mfma_f32_32x32x16_bf16 v[140:155], v[160:163], v[108:111], v[140:155]
	ds_read_b128 v[160:163], v227 offset:18432
	v_exp_f32_e32 v68, v68
	v_exp_f32_e32 v69, v69
	v_exp_f32_e32 v70, v70
	v_exp_f32_e32 v71, v71
	v_mfma_f32_32x32x16_bf16 v[140:155], v[228:231], v[112:115], v[140:155]
	ds_read_b128 v[228:231], v244 offset:18432
	v_exp_f32_e32 v72, v72
	v_exp_f32_e32 v73, v73
	v_exp_f32_e32 v74, v74
	v_exp_f32_e32 v75, v75
	v_mfma_f32_32x32x16_bf16 v[140:155], v[232:235], v[116:119], v[140:155]
	ds_read_b128 v[232:235], v245 offset:18432
	v_exp_f32_e32 v76, v76
	v_exp_f32_e32 v77, v77
	v_exp_f32_e32 v78, v78
	v_exp_f32_e32 v79, v79
	v_mfma_f32_32x32x16_bf16 v[140:155], v[236:239], v[120:123], v[140:155]
	ds_read_b128 v[236:239], v216 offset:18432
	v_cvt_pk_bf16_f32 v64, v64, v65
	v_cvt_pk_bf16_f32 v65, v66, v67
	v_cvt_pk_bf16_f32 v66, v68, v69
	v_cvt_pk_bf16_f32 v67, v70, v71
	v_mfma_f32_32x32x16_bf16 v[140:155], v[240:243], v[124:127], v[140:155]
	ds_read_b128 v[240:243], v192 offset:18432
	v_cvt_pk_bf16_f32 v68, v72, v73
	v_cvt_pk_bf16_f32 v69, v74, v75
	v_cvt_pk_bf16_f32 v70, v76, v77
	v_cvt_pk_bf16_f32 v71, v78, v79
	s_waitcnt lgkmcnt(12)
; #define MFMA32(a, b, c) __builtin_amdgcn_mfma_f32_32x32x16_bf16((a), (b), (c), 0, 0, 0)
; DI bf16x8 cat4(s16x4 lo, s16x4 hi) { return __builtin_shufflevector(lo, hi, 0, 1, 2, 3, 4, 5, 6, 7); }
; template <int DK>
; DI void attn_dense_item(const u16* __restrict__ Qh, const u16* __restrict__ Kh, const u16* __restrict__ Vh,
;                         const u16* __restrict__ gate, u16* __restrict__ yout, char* lds) {
;     ...
;     for (int kb = 0; kb < KT / 32; ++kb) {
;       f32x16 S0, S1;
; #pragma unroll
;       for (int i = 0; i < 16; ++i) { S0[i] = 0.f; S1[i] = 0.f; }
; #pragma unroll
;       for (int s = 0; s < NS; ++s) {
;         const bf16x8 kf = *(const bf16x8*)(buf + koff(kb * 32 + r32, 2 * s + h));
;         S0 = MFMA32(kf, qf[0][s], S0);
;         S1 = MFMA32(kf, qf[1][s], S1);
;       }
; #pragma unroll
;       for (int i = 0; i < 16; ++i) S0[i] = __builtin_amdgcn_exp2f(S0[i]);
; #pragma unroll
;       for (int i = 0; i < 16; ++i) S1[i] = __builtin_amdgcn_exp2f(S1[i]);
;       bf16x8 pf0[2], pf1[2];
; #pragma unroll
;       for (int st = 0; st < 2; ++st) {
;         pf0[st] = pack8(S0[8 * st], S0[8 * st + 1], S0[8 * st + 2], S0[8 * st + 3], S0[8 * st + 4], S0[8 * st + 5], S0[8 * st + 6], S0[8 * st + 7]);
;         pf1[st] = pack8(S1[8 * st], S1[8 * st + 1], S1[8 * st + 2], S1[8 * st + 3], S1[8 * st + 4], S1[8 * st + 5], S1[8 * st + 6], S1[8 * st + 7]);
;       }
; #pragma unroll
;       for (int st = 0; st < 2; ++st) {
;         L0 = __builtin_amdgcn_mfma_f32_16x16x32_bf16(aones, pf0[st], L0, 0, 0, 0);
;         L1 = __builtin_amdgcn_mfma_f32_16x16x32_bf16(aones, pf1[st], L1, 0, 0, 0);
;       }
; #pragma unroll
;       for (int st = 0; st < 2; ++st)
; #pragma unroll
;         for (int db = 0; db < 2; ++db) {
;           const char* vp = buf + vbase[db] + (kb * 32 + st * 16) * 128;
;           const bf16x8 vf = cat4(trread(vp), trread(vp + 8 * 128));
;           O[0][db] = MFMA32(vf, pf0[st], O[0][db]);
;           O[1][db] = MFMA32(vf, pf1[st], O[1][db]);
;         }
	v_mfma_f32_32x32x16_bf16 v[48:63], v[200:203], v[64:67], v[48:63]
	s_waitcnt lgkmcnt(10)
	v_mfma_f32_32x32x16_bf16 v[32:47], v[204:207], v[64:67], v[32:47]
	s_waitcnt lgkmcnt(8)
	v_mfma_f32_32x32x16_bf16 v[48:63], v[208:211], v[68:71], v[48:63]
	s_waitcnt lgkmcnt(6)
	v_mfma_f32_32x32x16_bf16 v[32:47], v[212:215], v[68:71], v[32:47]
	v_mfma_f32_16x16x32_bf16 v[136:139], v[128:131], v[64:67], v[136:139]
	v_mfma_f32_16x16x32_bf16 v[136:139], v[128:131], v[68:71], v[136:139]
	s_waitcnt lgkmcnt(5)
	v_mfma_f32_32x32x16_bf16 v[64:79], v[156:159], v[80:83], 0
	v_exp_f32_e32 v140, v140
	v_exp_f32_e32 v141, v141
	v_exp_f32_e32 v142, v142
	v_exp_f32_e32 v143, v143
	s_waitcnt lgkmcnt(4)
	v_mfma_f32_32x32x16_bf16 v[64:79], v[160:163], v[84:87], v[64:79]
	v_exp_f32_e32 v144, v144
	v_exp_f32_e32 v145, v145
	v_exp_f32_e32 v146, v146
	v_exp_f32_e32 v147, v147
	s_waitcnt lgkmcnt(3)
	v_mfma_f32_32x32x16_bf16 v[64:79], v[228:231], v[88:91], v[64:79]
	v_exp_f32_e32 v148, v148
	v_exp_f32_e32 v149, v149
	v_exp_f32_e32 v150, v150
	v_exp_f32_e32 v151, v151
	s_waitcnt lgkmcnt(2)
	v_mfma_f32_32x32x16_bf16 v[64:79], v[232:235], v[92:95], v[64:79]
	v_exp_f32_e32 v152, v152
	v_exp_f32_e32 v153, v153
	v_exp_f32_e32 v154, v154
	v_exp_f32_e32 v155, v155
	s_waitcnt lgkmcnt(1)
	v_mfma_f32_32x32x16_bf16 v[64:79], v[236:239], v[96:99], v[64:79]
	v_cvt_pk_bf16_f32 v140, v140, v141
	v_cvt_pk_bf16_f32 v141, v142, v143
	v_cvt_pk_bf16_f32 v142, v144, v145
	v_cvt_pk_bf16_f32 v143, v146, v147
	s_waitcnt lgkmcnt(0)
	v_mfma_f32_32x32x16_bf16 v[64:79], v[240:243], v[100:103], v[64:79]
	v_cvt_pk_bf16_f32 v144, v148, v149
	v_cvt_pk_bf16_f32 v145, v150, v151
	v_cvt_pk_bf16_f32 v146, v152, v153
	v_cvt_pk_bf16_f32 v147, v154, v155
	v_mfma_f32_32x32x16_bf16 v[16:31], v[200:203], v[140:143], v[16:31]
	ds_read_b64_tr_b16 v[200:201], v193 offset:28672
	ds_read_b64_tr_b16 v[202:203], v193 offset:29696
	v_mfma_f32_32x32x16_bf16 v[0:15], v[204:207], v[140:143], v[0:15]
	ds_read_b64_tr_b16 v[204:205], v199 offset:28672
	ds_read_b64_tr_b16 v[206:207], v199 offset:29696
	v_mfma_f32_32x32x16_bf16 v[16:31], v[208:211], v[144:147], v[16:31]
	ds_read_b64_tr_b16 v[208:209], v193 offset:30720
	ds_read_b64_tr_b16 v[210:211], v193 offset:31744
	v_mfma_f32_32x32x16_bf16 v[0:15], v[212:215], v[144:147], v[0:15]
	ds_read_b64_tr_b16 v[212:213], v199 offset:30720
	ds_read_b64_tr_b16 v[214:215], v199 offset:31744
	v_mfma_f32_16x16x32_bf16 v[132:135], v[128:131], v[140:143], v[132:135]
	v_mfma_f32_16x16x32_bf16 v[132:135], v[128:131], v[144:147], v[132:135]
	v_mfma_f32_32x32x16_bf16 v[140:155], v[156:159], v[104:107], 0
	ds_read_b128 v[156:159], v164 offset:24576
	v_exp_f32_e32 v64, v64
	v_exp_f32_e32 v65, v65
	v_exp_f32_e32 v66, v66
	v_exp_f32_e32 v67, v67
	v_mfma_f32_32x32x16_bf16 v[140:155], v[160:163], v[108:111], v[140:155]
	ds_read_b128 v[160:163], v227 offset:24576
	v_exp_f32_e32 v68, v68
	v_exp_f32_e32 v69, v69
	v_exp_f32_e32 v70, v70
	v_exp_f32_e32 v71, v71
	v_mfma_f32_32x32x16_bf16 v[140:155], v[228:231], v[112:115], v[140:155]
	ds_read_b128 v[228:231], v244 offset:24576
	v_exp_f32_e32 v72, v72
	v_exp_f32_e32 v73, v73
	v_exp_f32_e32 v74, v74
	v_exp_f32_e32 v75, v75
	v_mfma_f32_32x32x16_bf16 v[140:155], v[232:235], v[116:119], v[140:155]
	ds_read_b128 v[232:235], v245 offset:24576
	v_exp_f32_e32 v76, v76
	v_exp_f32_e32 v77, v77
	v_exp_f32_e32 v78, v78
	v_exp_f32_e32 v79, v79
	v_mfma_f32_32x32x16_bf16 v[140:155], v[236:239], v[120:123], v[140:155]
	ds_read_b128 v[236:239], v216 offset:24576
	v_cvt_pk_bf16_f32 v64, v64, v65
	v_cvt_pk_bf16_f32 v65, v66, v67
	v_cvt_pk_bf16_f32 v66, v68, v69
	v_cvt_pk_bf16_f32 v67, v70, v71
	v_mfma_f32_32x32x16_bf16 v[140:155], v[240:243], v[124:127], v[140:155]
	ds_read_b128 v[240:243], v192 offset:24576
	v_cvt_pk_bf16_f32 v68, v72, v73
	v_cvt_pk_bf16_f32 v69, v74, v75
	v_cvt_pk_bf16_f32 v70, v76, v77
	v_cvt_pk_bf16_f32 v71, v78, v79
	s_waitcnt lgkmcnt(12)
	v_mfma_f32_32x32x16_bf16 v[48:63], v[200:203], v[64:67], v[48:63]
	s_waitcnt lgkmcnt(10)
	v_mfma_f32_32x32x16_bf16 v[32:47], v[204:207], v[64:67], v[32:47]
	s_waitcnt lgkmcnt(8)
	v_mfma_f32_32x32x16_bf16 v[48:63], v[208:211], v[68:71], v[48:63]
	s_waitcnt lgkmcnt(6)
	v_mfma_f32_32x32x16_bf16 v[32:47], v[212:215], v[68:71], v[32:47]
	v_mfma_f32_16x16x32_bf16 v[136:139], v[128:131], v[64:67], v[136:139]
	v_mfma_f32_16x16x32_bf16 v[136:139], v[128:131], v[68:71], v[136:139]
	s_waitcnt lgkmcnt(5)
	v_mfma_f32_32x32x16_bf16 v[64:79], v[156:159], v[80:83], 0
	v_exp_f32_e32 v140, v140
	v_exp_f32_e32 v141, v141
	v_exp_f32_e32 v142, v142
	v_exp_f32_e32 v143, v143
	s_waitcnt lgkmcnt(4)
	v_mfma_f32_32x32x16_bf16 v[64:79], v[160:163], v[84:87], v[64:79]
	v_exp_f32_e32 v144, v144
	v_exp_f32_e32 v145, v145
	v_exp_f32_e32 v146, v146
	v_exp_f32_e32 v147, v147
	s_waitcnt lgkmcnt(3)
	v_mfma_f32_32x32x16_bf16 v[64:79], v[228:231], v[88:91], v[64:79]
	v_exp_f32_e32 v148, v148
	v_exp_f32_e32 v149, v149
	v_exp_f32_e32 v150, v150
	v_exp_f32_e32 v151, v151
	s_waitcnt lgkmcnt(2)
	v_mfma_f32_32x32x16_bf16 v[64:79], v[232:235], v[92:95], v[64:79]
	v_exp_f32_e32 v152, v152
	v_exp_f32_e32 v153, v153
	v_exp_f32_e32 v154, v154
	v_exp_f32_e32 v155, v155
	s_waitcnt lgkmcnt(1)
	v_mfma_f32_32x32x16_bf16 v[64:79], v[236:239], v[96:99], v[64:79]
	v_cvt_pk_bf16_f32 v140, v140, v141
	v_cvt_pk_bf16_f32 v141, v142, v143
	v_cvt_pk_bf16_f32 v142, v144, v145
	v_cvt_pk_bf16_f32 v143, v146, v147
	s_waitcnt lgkmcnt(0)
; #define MFMA32(a, b, c) __builtin_amdgcn_mfma_f32_32x32x16_bf16((a), (b), (c), 0, 0, 0)
; DI bf16x8 cat4(s16x4 lo, s16x4 hi) { return __builtin_shufflevector(lo, hi, 0, 1, 2, 3, 4, 5, 6, 7); }
; template <int DK>
; DI void attn_dense_item(const u16* __restrict__ Qh, const u16* __restrict__ Kh, const u16* __restrict__ Vh,
;                         const u16* __restrict__ gate, u16* __restrict__ yout, char* lds) {
;     ...
;     for (int kb = 0; kb < KT / 32; ++kb) {
;       f32x16 S0, S1;
; #pragma unroll
;       for (int i = 0; i < 16; ++i) { S0[i] = 0.f; S1[i] = 0.f; }
; #pragma unroll
;       for (int s = 0; s < NS; ++s) {
;         const bf16x8 kf = *(const bf16x8*)(buf + koff(kb * 32 + r32, 2 * s + h));
;         S0 = MFMA32(kf, qf[0][s], S0);
;         S1 = MFMA32(kf, qf[1][s], S1);
;       }
; #pragma unroll
;       for (int i = 0; i < 16; ++i) S0[i] = __builtin_amdgcn_exp2f(S0[i]);
; #pragma unroll
;       for (int i = 0; i < 16; ++i) S1[i] = __builtin_amdgcn_exp2f(S1[i]);
;       bf16x8 pf0[2], pf1[2];
; #pragma unroll
;       for (int st = 0; st < 2; ++st) {
;         pf0[st] = pack8(S0[8 * st], S0[8 * st + 1], S0[8 * st + 2], S0[8 * st + 3], S0[8 * st + 4], S0[8 * st + 5], S0[8 * st + 6], S0[8 * st + 7]);
;         pf1[st] = pack8(S1[8 * st], S1[8 * st + 1], S1[8 * st + 2], S1[8 * st + 3], S1[8 * st + 4], S1[8 * st + 5], S1[8 * st + 6], S1[8 * st + 7]);
;       }
; #pragma unroll
;       for (int st = 0; st < 2; ++st) {
;         L0 = __builtin_amdgcn_mfma_f32_16x16x32_bf16(aones, pf0[st], L0, 0, 0, 0);
;         L1 = __builtin_amdgcn_mfma_f32_16x16x32_bf16(aones, pf1[st], L1, 0, 0, 0);
;       }
; #pragma unroll
;       for (int st = 0; st < 2; ++st)
; #pragma unroll
;         for (int db = 0; db < 2; ++db) {
;           const char* vp = buf + vbase[db] + (kb * 32 + st * 16) * 128;
;           const bf16x8 vf = cat4(trread(vp), trread(vp + 8 * 128));
;           O[0][db] = MFMA32(vf, pf0[st], O[0][db]);
;           O[1][db] = MFMA32(vf, pf1[st], O[1][db]);
;         }
	v_mfma_f32_32x32x16_bf16 v[64:79], v[240:243], v[100:103], v[64:79]
	v_cvt_pk_bf16_f32 v144, v148, v149
	v_cvt_pk_bf16_f32 v145, v150, v151
	v_cvt_pk_bf16_f32 v146, v152, v153
	v_cvt_pk_bf16_f32 v147, v154, v155
	v_mfma_f32_32x32x16_bf16 v[16:31], v[200:203], v[140:143], v[16:31]
	ds_read_b64_tr_b16 v[200:201], v193 offset:32768
	ds_read_b64_tr_b16 v[202:203], v193 offset:33792
	v_mfma_f32_32x32x16_bf16 v[0:15], v[204:207], v[140:143], v[0:15]
	ds_read_b64_tr_b16 v[204:205], v199 offset:32768
	ds_read_b64_tr_b16 v[206:207], v199 offset:33792
	v_mfma_f32_32x32x16_bf16 v[16:31], v[208:211], v[144:147], v[16:31]
	ds_read_b64_tr_b16 v[208:209], v193 offset:34816
	ds_read_b64_tr_b16 v[210:211], v193 offset:35840
	v_mfma_f32_32x32x16_bf16 v[0:15], v[212:215], v[144:147], v[0:15]
	ds_read_b64_tr_b16 v[212:213], v199 offset:34816
	ds_read_b64_tr_b16 v[214:215], v199 offset:35840
	v_mfma_f32_16x16x32_bf16 v[132:135], v[128:131], v[140:143], v[132:135]
	v_mfma_f32_16x16x32_bf16 v[132:135], v[128:131], v[144:147], v[132:135]
	v_mfma_f32_32x32x16_bf16 v[140:155], v[156:159], v[104:107], 0
	ds_read_b128 v[156:159], v164 offset:30720
	v_exp_f32_e32 v64, v64
	v_exp_f32_e32 v65, v65
	v_exp_f32_e32 v66, v66
	v_exp_f32_e32 v67, v67
	v_mfma_f32_32x32x16_bf16 v[140:155], v[160:163], v[108:111], v[140:155]
	ds_read_b128 v[160:163], v227 offset:30720
	v_exp_f32_e32 v68, v68
	v_exp_f32_e32 v69, v69
	v_exp_f32_e32 v70, v70
	v_exp_f32_e32 v71, v71
	v_mfma_f32_32x32x16_bf16 v[140:155], v[228:231], v[112:115], v[140:155]
	ds_read_b128 v[228:231], v244 offset:30720
	v_exp_f32_e32 v72, v72
	v_exp_f32_e32 v73, v73
	v_exp_f32_e32 v74, v74
	v_exp_f32_e32 v75, v75
	v_mfma_f32_32x32x16_bf16 v[140:155], v[232:235], v[116:119], v[140:155]
	ds_read_b128 v[232:235], v245 offset:30720
	v_exp_f32_e32 v76, v76
	v_exp_f32_e32 v77, v77
	v_exp_f32_e32 v78, v78
	v_exp_f32_e32 v79, v79
	v_mfma_f32_32x32x16_bf16 v[140:155], v[236:239], v[120:123], v[140:155]
	ds_read_b128 v[236:239], v216 offset:30720
	v_cvt_pk_bf16_f32 v64, v64, v65
	v_cvt_pk_bf16_f32 v65, v66, v67
	v_cvt_pk_bf16_f32 v66, v68, v69
	v_cvt_pk_bf16_f32 v67, v70, v71
	v_mfma_f32_32x32x16_bf16 v[140:155], v[240:243], v[124:127], v[140:155]
	ds_read_b128 v[240:243], v192 offset:30720
	v_cvt_pk_bf16_f32 v68, v72, v73
	v_cvt_pk_bf16_f32 v69, v74, v75
	v_cvt_pk_bf16_f32 v70, v76, v77
	v_cvt_pk_bf16_f32 v71, v78, v79
	s_waitcnt lgkmcnt(12)
	v_mfma_f32_32x32x16_bf16 v[48:63], v[200:203], v[64:67], v[48:63]
	s_waitcnt lgkmcnt(10)
	v_mfma_f32_32x32x16_bf16 v[32:47], v[204:207], v[64:67], v[32:47]
	s_waitcnt lgkmcnt(8)
	v_mfma_f32_32x32x16_bf16 v[48:63], v[208:211], v[68:71], v[48:63]
	s_waitcnt lgkmcnt(6)
	v_mfma_f32_32x32x16_bf16 v[32:47], v[212:215], v[68:71], v[32:47]
	v_mfma_f32_16x16x32_bf16 v[136:139], v[128:131], v[64:67], v[136:139]
	v_mfma_f32_16x16x32_bf16 v[136:139], v[128:131], v[68:71], v[136:139]
	s_waitcnt lgkmcnt(5)
	v_mfma_f32_32x32x16_bf16 v[64:79], v[156:159], v[80:83], 0
	v_exp_f32_e32 v140, v140
	v_exp_f32_e32 v141, v141
	v_exp_f32_e32 v142, v142
	v_exp_f32_e32 v143, v143
	s_waitcnt lgkmcnt(4)
	v_mfma_f32_32x32x16_bf16 v[64:79], v[160:163], v[84:87], v[64:79]
	v_exp_f32_e32 v144, v144
	v_exp_f32_e32 v145, v145
	v_exp_f32_e32 v146, v146
	v_exp_f32_e32 v147, v147
	s_waitcnt lgkmcnt(3)
	v_mfma_f32_32x32x16_bf16 v[64:79], v[228:231], v[88:91], v[64:79]
	v_exp_f32_e32 v148, v148
	v_exp_f32_e32 v149, v149
	v_exp_f32_e32 v150, v150
	v_exp_f32_e32 v151, v151
	s_waitcnt lgkmcnt(2)
	v_mfma_f32_32x32x16_bf16 v[64:79], v[232:235], v[92:95], v[64:79]
	v_exp_f32_e32 v152, v152
	v_exp_f32_e32 v153, v153
	v_exp_f32_e32 v154, v154
	v_exp_f32_e32 v155, v155
	s_waitcnt lgkmcnt(1)
	v_mfma_f32_32x32x16_bf16 v[64:79], v[236:239], v[96:99], v[64:79]
	v_cvt_pk_bf16_f32 v140, v140, v141
	v_cvt_pk_bf16_f32 v141, v142, v143
	v_cvt_pk_bf16_f32 v142, v144, v145
	v_cvt_pk_bf16_f32 v143, v146, v147
	s_waitcnt lgkmcnt(0)
	v_mfma_f32_32x32x16_bf16 v[64:79], v[240:243], v[100:103], v[64:79]
	v_cvt_pk_bf16_f32 v144, v148, v149
	v_cvt_pk_bf16_f32 v145, v150, v151
	v_cvt_pk_bf16_f32 v146, v152, v153
	v_cvt_pk_bf16_f32 v147, v154, v155
	v_mfma_f32_32x32x16_bf16 v[16:31], v[200:203], v[140:143], v[16:31]
	ds_read_b64_tr_b16 v[200:201], v193 offset:36864
	ds_read_b64_tr_b16 v[202:203], v193 offset:37888
	v_mfma_f32_32x32x16_bf16 v[0:15], v[204:207], v[140:143], v[0:15]
	ds_read_b64_tr_b16 v[204:205], v199 offset:36864
	ds_read_b64_tr_b16 v[206:207], v199 offset:37888
	v_mfma_f32_32x32x16_bf16 v[16:31], v[208:211], v[144:147], v[16:31]
	ds_read_b64_tr_b16 v[208:209], v193 offset:38912
	ds_read_b64_tr_b16 v[210:211], v193 offset:39936
	v_mfma_f32_32x32x16_bf16 v[0:15], v[212:215], v[144:147], v[0:15]
	ds_read_b64_tr_b16 v[212:213], v199 offset:38912
	ds_read_b64_tr_b16 v[214:215], v199 offset:39936
	v_mfma_f32_16x16x32_bf16 v[132:135], v[128:131], v[140:143], v[132:135]
	v_mfma_f32_16x16x32_bf16 v[132:135], v[128:131], v[144:147], v[132:135]
	v_mfma_f32_32x32x16_bf16 v[140:155], v[156:159], v[104:107], 0
	ds_read_b128 v[156:159], v164 offset:36864
	v_exp_f32_e32 v64, v64
	v_exp_f32_e32 v65, v65
	v_exp_f32_e32 v66, v66
	v_exp_f32_e32 v67, v67
	v_mfma_f32_32x32x16_bf16 v[140:155], v[160:163], v[108:111], v[140:155]
	ds_read_b128 v[160:163], v227 offset:36864
	v_exp_f32_e32 v68, v68
	v_exp_f32_e32 v69, v69
	v_exp_f32_e32 v70, v70
	v_exp_f32_e32 v71, v71
	v_mfma_f32_32x32x16_bf16 v[140:155], v[228:231], v[112:115], v[140:155]
	ds_read_b128 v[228:231], v244 offset:36864
	v_exp_f32_e32 v72, v72
	v_exp_f32_e32 v73, v73
	v_exp_f32_e32 v74, v74
	v_exp_f32_e32 v75, v75
	v_mfma_f32_32x32x16_bf16 v[140:155], v[232:235], v[116:119], v[140:155]
	ds_read_b128 v[232:235], v245 offset:36864
	v_exp_f32_e32 v76, v76
	v_exp_f32_e32 v77, v77
	v_exp_f32_e32 v78, v78
	v_exp_f32_e32 v79, v79
	v_mfma_f32_32x32x16_bf16 v[140:155], v[236:239], v[120:123], v[140:155]
	ds_read_b128 v[236:239], v216 offset:36864
	v_cvt_pk_bf16_f32 v64, v64, v65
	v_cvt_pk_bf16_f32 v65, v66, v67
	v_cvt_pk_bf16_f32 v66, v68, v69
	v_cvt_pk_bf16_f32 v67, v70, v71
	v_mfma_f32_32x32x16_bf16 v[140:155], v[240:243], v[124:127], v[140:155]
	ds_read_b128 v[240:243], v192 offset:36864
	v_cvt_pk_bf16_f32 v68, v72, v73
	v_cvt_pk_bf16_f32 v69, v74, v75
	v_cvt_pk_bf16_f32 v70, v76, v77
	v_cvt_pk_bf16_f32 v71, v78, v79
	s_waitcnt lgkmcnt(12)
; #define MFMA32(a, b, c) __builtin_amdgcn_mfma_f32_32x32x16_bf16((a), (b), (c), 0, 0, 0)
; DI bf16x8 cat4(s16x4 lo, s16x4 hi) { return __builtin_shufflevector(lo, hi, 0, 1, 2, 3, 4, 5, 6, 7); }
; template <int DK>
; DI void attn_dense_item(const u16* __restrict__ Qh, const u16* __restrict__ Kh, const u16* __restrict__ Vh,
;                         const u16* __restrict__ gate, u16* __restrict__ yout, char* lds) {
;     ...
;     for (int kb = 0; kb < KT / 32; ++kb) {
;       f32x16 S0, S1;
; #pragma unroll
;       for (int i = 0; i < 16; ++i) { S0[i] = 0.f; S1[i] = 0.f; }
; #pragma unroll
;       for (int s = 0; s < NS; ++s) {
;         const bf16x8 kf = *(const bf16x8*)(buf + koff(kb * 32 + r32, 2 * s + h));
;         S0 = MFMA32(kf, qf[0][s], S0);
;         S1 = MFMA32(kf, qf[1][s], S1);
;       }
; #pragma unroll
;       for (int i = 0; i < 16; ++i) S0[i] = __builtin_amdgcn_exp2f(S0[i]);
; #pragma unroll
;       for (int i = 0; i < 16; ++i) S1[i] = __builtin_amdgcn_exp2f(S1[i]);
;       bf16x8 pf0[2], pf1[2];
; #pragma unroll
;       for (int st = 0; st < 2; ++st) {
;         pf0[st] = pack8(S0[8 * st], S0[8 * st + 1], S0[8 * st + 2], S0[8 * st + 3], S0[8 * st + 4], S0[8 * st + 5], S0[8 * st + 6], S0[8 * st + 7]);
;         pf1[st] = pack8(S1[8 * st], S1[8 * st + 1], S1[8 * st + 2], S1[8 * st + 3], S1[8 * st + 4], S1[8 * st + 5], S1[8 * st + 6], S1[8 * st + 7]);
;       }
; #pragma unroll
;       for (int st = 0; st < 2; ++st) {
;         L0 = __builtin_amdgcn_mfma_f32_16x16x32_bf16(aones, pf0[st], L0, 0, 0, 0);
;         L1 = __builtin_amdgcn_mfma_f32_16x16x32_bf16(aones, pf1[st], L1, 0, 0, 0);
;       }
; #pragma unroll
;       for (int st = 0; st < 2; ++st)
; #pragma unroll
;         for (int db = 0; db < 2; ++db) {
;           const char* vp = buf + vbase[db] + (kb * 32 + st * 16) * 128;
;           const bf16x8 vf = cat4(trread(vp), trread(vp + 8 * 128));
;           O[0][db] = MFMA32(vf, pf0[st], O[0][db]);
;           O[1][db] = MFMA32(vf, pf1[st], O[1][db]);
;         }
	v_mfma_f32_32x32x16_bf16 v[48:63], v[200:203], v[64:67], v[48:63]
	s_waitcnt lgkmcnt(10)
	v_mfma_f32_32x32x16_bf16 v[32:47], v[204:207], v[64:67], v[32:47]
	s_waitcnt lgkmcnt(8)
	v_mfma_f32_32x32x16_bf16 v[48:63], v[208:211], v[68:71], v[48:63]
	s_waitcnt lgkmcnt(6)
	v_mfma_f32_32x32x16_bf16 v[32:47], v[212:215], v[68:71], v[32:47]
	v_mfma_f32_16x16x32_bf16 v[136:139], v[128:131], v[64:67], v[136:139]
	v_mfma_f32_16x16x32_bf16 v[136:139], v[128:131], v[68:71], v[136:139]
	s_waitcnt lgkmcnt(5)
	v_mfma_f32_32x32x16_bf16 v[64:79], v[156:159], v[80:83], 0
	v_exp_f32_e32 v140, v140
	v_exp_f32_e32 v141, v141
	v_exp_f32_e32 v142, v142
	v_exp_f32_e32 v143, v143
	s_waitcnt lgkmcnt(4)
	v_mfma_f32_32x32x16_bf16 v[64:79], v[160:163], v[84:87], v[64:79]
	v_exp_f32_e32 v144, v144
	v_exp_f32_e32 v145, v145
	v_exp_f32_e32 v146, v146
	v_exp_f32_e32 v147, v147
	s_waitcnt lgkmcnt(3)
	v_mfma_f32_32x32x16_bf16 v[64:79], v[228:231], v[88:91], v[64:79]
	v_exp_f32_e32 v148, v148
	v_exp_f32_e32 v149, v149
	v_exp_f32_e32 v150, v150
	v_exp_f32_e32 v151, v151
	s_waitcnt lgkmcnt(2)
	v_mfma_f32_32x32x16_bf16 v[64:79], v[232:235], v[92:95], v[64:79]
	v_exp_f32_e32 v152, v152
	v_exp_f32_e32 v153, v153
	v_exp_f32_e32 v154, v154
	v_exp_f32_e32 v155, v155
	s_waitcnt lgkmcnt(1)
	v_mfma_f32_32x32x16_bf16 v[64:79], v[236:239], v[96:99], v[64:79]
	v_cvt_pk_bf16_f32 v140, v140, v141
	v_cvt_pk_bf16_f32 v141, v142, v143
	v_cvt_pk_bf16_f32 v142, v144, v145
	v_cvt_pk_bf16_f32 v143, v146, v147
	s_waitcnt lgkmcnt(0)
	v_mfma_f32_32x32x16_bf16 v[64:79], v[240:243], v[100:103], v[64:79]
	v_cvt_pk_bf16_f32 v144, v148, v149
	v_cvt_pk_bf16_f32 v145, v150, v151
	v_cvt_pk_bf16_f32 v146, v152, v153
	v_cvt_pk_bf16_f32 v147, v154, v155
	v_mfma_f32_32x32x16_bf16 v[16:31], v[200:203], v[140:143], v[16:31]
	ds_read_b64_tr_b16 v[200:201], v193 offset:40960
	ds_read_b64_tr_b16 v[202:203], v193 offset:41984
	v_mfma_f32_32x32x16_bf16 v[0:15], v[204:207], v[140:143], v[0:15]
	ds_read_b64_tr_b16 v[204:205], v199 offset:40960
	ds_read_b64_tr_b16 v[206:207], v199 offset:41984
	v_mfma_f32_32x32x16_bf16 v[16:31], v[208:211], v[144:147], v[16:31]
	ds_read_b64_tr_b16 v[208:209], v193 offset:43008
	ds_read_b64_tr_b16 v[210:211], v193 offset:44032
	v_mfma_f32_32x32x16_bf16 v[0:15], v[212:215], v[144:147], v[0:15]
	ds_read_b64_tr_b16 v[212:213], v199 offset:43008
	ds_read_b64_tr_b16 v[214:215], v199 offset:44032
	v_mfma_f32_16x16x32_bf16 v[132:135], v[128:131], v[140:143], v[132:135]
	v_mfma_f32_16x16x32_bf16 v[132:135], v[128:131], v[144:147], v[132:135]
	v_mfma_f32_32x32x16_bf16 v[140:155], v[156:159], v[104:107], 0
	ds_read_b128 v[156:159], v164 offset:43008
	v_exp_f32_e32 v64, v64
	v_exp_f32_e32 v65, v65
	v_exp_f32_e32 v66, v66
	v_exp_f32_e32 v67, v67
	v_mfma_f32_32x32x16_bf16 v[140:155], v[160:163], v[108:111], v[140:155]
	ds_read_b128 v[160:163], v227 offset:43008
	v_exp_f32_e32 v68, v68
	v_exp_f32_e32 v69, v69
	v_exp_f32_e32 v70, v70
	v_exp_f32_e32 v71, v71
	v_mfma_f32_32x32x16_bf16 v[140:155], v[228:231], v[112:115], v[140:155]
	ds_read_b128 v[228:231], v244 offset:43008
	v_exp_f32_e32 v72, v72
	v_exp_f32_e32 v73, v73
	v_exp_f32_e32 v74, v74
	v_exp_f32_e32 v75, v75
	v_mfma_f32_32x32x16_bf16 v[140:155], v[232:235], v[116:119], v[140:155]
	ds_read_b128 v[232:235], v245 offset:43008
	v_exp_f32_e32 v76, v76
	v_exp_f32_e32 v77, v77
	v_exp_f32_e32 v78, v78
	v_exp_f32_e32 v79, v79
	v_mfma_f32_32x32x16_bf16 v[140:155], v[236:239], v[120:123], v[140:155]
	ds_read_b128 v[236:239], v216 offset:43008
	v_cvt_pk_bf16_f32 v64, v64, v65
	v_cvt_pk_bf16_f32 v65, v66, v67
	v_cvt_pk_bf16_f32 v66, v68, v69
	v_cvt_pk_bf16_f32 v67, v70, v71
	v_mfma_f32_32x32x16_bf16 v[140:155], v[240:243], v[124:127], v[140:155]
	ds_read_b128 v[240:243], v192 offset:43008
	v_cvt_pk_bf16_f32 v68, v72, v73
	v_cvt_pk_bf16_f32 v69, v74, v75
	v_cvt_pk_bf16_f32 v70, v76, v77
	v_cvt_pk_bf16_f32 v71, v78, v79
	s_waitcnt lgkmcnt(12)
	v_mfma_f32_32x32x16_bf16 v[48:63], v[200:203], v[64:67], v[48:63]
	s_waitcnt lgkmcnt(10)
	v_mfma_f32_32x32x16_bf16 v[32:47], v[204:207], v[64:67], v[32:47]
	s_waitcnt lgkmcnt(8)
	v_mfma_f32_32x32x16_bf16 v[48:63], v[208:211], v[68:71], v[48:63]
	s_waitcnt lgkmcnt(6)
	v_mfma_f32_32x32x16_bf16 v[32:47], v[212:215], v[68:71], v[32:47]
	v_mfma_f32_16x16x32_bf16 v[136:139], v[128:131], v[64:67], v[136:139]
	v_mfma_f32_16x16x32_bf16 v[136:139], v[128:131], v[68:71], v[136:139]
	s_waitcnt lgkmcnt(5)
	v_mfma_f32_32x32x16_bf16 v[64:79], v[156:159], v[80:83], 0
	v_exp_f32_e32 v140, v140
	v_exp_f32_e32 v141, v141
	v_exp_f32_e32 v142, v142
	v_exp_f32_e32 v143, v143
	s_waitcnt lgkmcnt(4)
; #define MFMA32(a, b, c) __builtin_amdgcn_mfma_f32_32x32x16_bf16((a), (b), (c), 0, 0, 0)
; DI bf16x8 cat4(s16x4 lo, s16x4 hi) { return __builtin_shufflevector(lo, hi, 0, 1, 2, 3, 4, 5, 6, 7); }
; template <int DK>
; DI void attn_dense_item(const u16* __restrict__ Qh, const u16* __restrict__ Kh, const u16* __restrict__ Vh,
;                         const u16* __restrict__ gate, u16* __restrict__ yout, char* lds) {
;     ...
;     for (int kb = 0; kb < KT / 32; ++kb) {
;       f32x16 S0, S1;
; #pragma unroll
;       for (int i = 0; i < 16; ++i) { S0[i] = 0.f; S1[i] = 0.f; }
; #pragma unroll
;       for (int s = 0; s < NS; ++s) {
;         const bf16x8 kf = *(const bf16x8*)(buf + koff(kb * 32 + r32, 2 * s + h));
;         S0 = MFMA32(kf, qf[0][s], S0);
;         S1 = MFMA32(kf, qf[1][s], S1);
;       }
; #pragma unroll
;       for (int i = 0; i < 16; ++i) S0[i] = __builtin_amdgcn_exp2f(S0[i]);
; #pragma unroll
;       for (int i = 0; i < 16; ++i) S1[i] = __builtin_amdgcn_exp2f(S1[i]);
;       bf16x8 pf0[2], pf1[2];
; #pragma unroll
;       for (int st = 0; st < 2; ++st) {
;         pf0[st] = pack8(S0[8 * st], S0[8 * st + 1], S0[8 * st + 2], S0[8 * st + 3], S0[8 * st + 4], S0[8 * st + 5], S0[8 * st + 6], S0[8 * st + 7]);
;         pf1[st] = pack8(S1[8 * st], S1[8 * st + 1], S1[8 * st + 2], S1[8 * st + 3], S1[8 * st + 4], S1[8 * st + 5], S1[8 * st + 6], S1[8 * st + 7]);
;       }
; #pragma unroll
;       for (int st = 0; st < 2; ++st) {
;         L0 = __builtin_amdgcn_mfma_f32_16x16x32_bf16(aones, pf0[st], L0, 0, 0, 0);
;         L1 = __builtin_amdgcn_mfma_f32_16x16x32_bf16(aones, pf1[st], L1, 0, 0, 0);
;       }
; #pragma unroll
;       for (int st = 0; st < 2; ++st)
; #pragma unroll
;         for (int db = 0; db < 2; ++db) {
;           const char* vp = buf + vbase[db] + (kb * 32 + st * 16) * 128;
;           const bf16x8 vf = cat4(trread(vp), trread(vp + 8 * 128));
;           O[0][db] = MFMA32(vf, pf0[st], O[0][db]);
;           O[1][db] = MFMA32(vf, pf1[st], O[1][db]);
;         }
;     }
	v_mfma_f32_32x32x16_bf16 v[64:79], v[160:163], v[84:87], v[64:79]
	v_exp_f32_e32 v144, v144
	v_exp_f32_e32 v145, v145
	v_exp_f32_e32 v146, v146
	v_exp_f32_e32 v147, v147
	s_waitcnt lgkmcnt(3)
	v_mfma_f32_32x32x16_bf16 v[64:79], v[228:231], v[88:91], v[64:79]
	v_exp_f32_e32 v148, v148
	v_exp_f32_e32 v149, v149
	v_exp_f32_e32 v150, v150
	v_exp_f32_e32 v151, v151
	s_waitcnt lgkmcnt(2)
	v_mfma_f32_32x32x16_bf16 v[64:79], v[232:235], v[92:95], v[64:79]
	v_exp_f32_e32 v152, v152
	v_exp_f32_e32 v153, v153
	v_exp_f32_e32 v154, v154
	v_exp_f32_e32 v155, v155
	s_waitcnt lgkmcnt(1)
	v_mfma_f32_32x32x16_bf16 v[64:79], v[236:239], v[96:99], v[64:79]
	v_cvt_pk_bf16_f32 v140, v140, v141
	v_cvt_pk_bf16_f32 v141, v142, v143
	v_cvt_pk_bf16_f32 v142, v144, v145
	v_cvt_pk_bf16_f32 v143, v146, v147
	s_waitcnt lgkmcnt(0)
	v_mfma_f32_32x32x16_bf16 v[64:79], v[240:243], v[100:103], v[64:79]
	v_cvt_pk_bf16_f32 v144, v148, v149
	v_cvt_pk_bf16_f32 v145, v150, v151
	v_cvt_pk_bf16_f32 v146, v152, v153
	v_cvt_pk_bf16_f32 v147, v154, v155
	v_mfma_f32_32x32x16_bf16 v[16:31], v[200:203], v[140:143], v[16:31]
	ds_read_b64_tr_b16 v[200:201], v193 offset:45056
	ds_read_b64_tr_b16 v[202:203], v193 offset:46080
	v_mfma_f32_32x32x16_bf16 v[0:15], v[204:207], v[140:143], v[0:15]
	ds_read_b64_tr_b16 v[204:205], v199 offset:45056
	ds_read_b64_tr_b16 v[206:207], v199 offset:46080
	v_mfma_f32_32x32x16_bf16 v[16:31], v[208:211], v[144:147], v[16:31]
	ds_read_b64_tr_b16 v[208:209], v193 offset:47104
	ds_read_b64_tr_b16 v[210:211], v193 offset:48128
	v_mfma_f32_32x32x16_bf16 v[0:15], v[212:215], v[144:147], v[0:15]
	ds_read_b64_tr_b16 v[212:213], v199 offset:47104
	ds_read_b64_tr_b16 v[214:215], v199 offset:48128
	v_mfma_f32_16x16x32_bf16 v[132:135], v[128:131], v[140:143], v[132:135]
	v_mfma_f32_16x16x32_bf16 v[132:135], v[128:131], v[144:147], v[132:135]
	v_mfma_f32_32x32x16_bf16 v[140:155], v[156:159], v[104:107], 0
	v_exp_f32_e32 v64, v64
	v_exp_f32_e32 v65, v65
	v_exp_f32_e32 v66, v66
	v_exp_f32_e32 v67, v67
	v_mfma_f32_32x32x16_bf16 v[140:155], v[160:163], v[108:111], v[140:155]
	v_exp_f32_e32 v68, v68
	v_exp_f32_e32 v69, v69
	v_exp_f32_e32 v70, v70
	v_exp_f32_e32 v71, v71
	v_mfma_f32_32x32x16_bf16 v[140:155], v[228:231], v[112:115], v[140:155]
	v_exp_f32_e32 v72, v72
	v_exp_f32_e32 v73, v73
	v_exp_f32_e32 v74, v74
	v_exp_f32_e32 v75, v75
	v_mfma_f32_32x32x16_bf16 v[140:155], v[232:235], v[116:119], v[140:155]
	v_exp_f32_e32 v76, v76
	v_exp_f32_e32 v77, v77
	v_exp_f32_e32 v78, v78
	v_exp_f32_e32 v79, v79
	v_mfma_f32_32x32x16_bf16 v[140:155], v[236:239], v[120:123], v[140:155]
	v_cvt_pk_bf16_f32 v64, v64, v65
	v_cvt_pk_bf16_f32 v65, v66, v67
	v_cvt_pk_bf16_f32 v66, v68, v69
	v_cvt_pk_bf16_f32 v67, v70, v71
	v_mfma_f32_32x32x16_bf16 v[140:155], v[240:243], v[124:127], v[140:155]
	v_cvt_pk_bf16_f32 v68, v72, v73
	v_cvt_pk_bf16_f32 v69, v74, v75
	v_cvt_pk_bf16_f32 v70, v76, v77
	v_cvt_pk_bf16_f32 v71, v78, v79
	s_waitcnt lgkmcnt(6)
	v_mfma_f32_32x32x16_bf16 v[48:63], v[200:203], v[64:67], v[48:63]
	s_waitcnt lgkmcnt(4)
	v_mfma_f32_32x32x16_bf16 v[32:47], v[204:207], v[64:67], v[32:47]
	s_waitcnt lgkmcnt(2)
	v_mfma_f32_32x32x16_bf16 v[48:63], v[208:211], v[68:71], v[48:63]
	s_waitcnt lgkmcnt(0)
	v_mfma_f32_32x32x16_bf16 v[32:47], v[212:215], v[68:71], v[32:47]
	v_mfma_f32_16x16x32_bf16 v[136:139], v[128:131], v[64:67], v[136:139]
	v_mfma_f32_16x16x32_bf16 v[136:139], v[128:131], v[68:71], v[136:139]
	s_nop 1
	v_exp_f32_e32 v140, v140
	v_exp_f32_e32 v141, v141
	v_exp_f32_e32 v142, v142
	v_exp_f32_e32 v143, v143
	v_exp_f32_e32 v144, v144
	v_exp_f32_e32 v145, v145
	v_exp_f32_e32 v146, v146
	v_exp_f32_e32 v147, v147
	v_exp_f32_e32 v148, v148
	v_exp_f32_e32 v149, v149
	v_exp_f32_e32 v150, v150
	v_exp_f32_e32 v151, v151
	v_exp_f32_e32 v152, v152
	v_exp_f32_e32 v153, v153
	v_exp_f32_e32 v154, v154
	v_exp_f32_e32 v155, v155
	v_cvt_pk_bf16_f32 v140, v140, v141
	v_cvt_pk_bf16_f32 v141, v142, v143
	v_cvt_pk_bf16_f32 v142, v144, v145
	v_cvt_pk_bf16_f32 v143, v146, v147
	v_cvt_pk_bf16_f32 v144, v148, v149
	v_cvt_pk_bf16_f32 v145, v150, v151
	v_cvt_pk_bf16_f32 v146, v152, v153
	v_cvt_pk_bf16_f32 v147, v154, v155
	s_nop 1
	v_mfma_f32_32x32x16_bf16 v[16:31], v[200:203], v[140:143], v[16:31]
	v_mfma_f32_32x32x16_bf16 v[0:15], v[204:207], v[140:143], v[0:15]
	v_mfma_f32_32x32x16_bf16 v[16:31], v[208:211], v[144:147], v[16:31]
	v_mfma_f32_32x32x16_bf16 v[0:15], v[212:215], v[144:147], v[0:15]
	v_mfma_f32_16x16x32_bf16 v[132:135], v[128:131], v[140:143], v[132:135]
	v_mfma_f32_16x16x32_bf16 v[132:135], v[128:131], v[144:147], v[132:135]
	s_cmp_lg_u32 s0, 0
	s_mov_b32 s3, s1
	s_cbranch_scc0 .LBB0_112
